# nt hint on the once-read f32 input loads of phase 0 (x_prompt/x_sample pass), on v20
# baseline (speedup 1.0000x reference)
; __device__ __forceinline__ unsigned pk2(float lo, float hi) { unsigned r; asm volatile("v_cvt_pk_bf16_f32 %0, %1, %2" : "=v"(r) : "v"(lo), "v"(hi)); return r; }
; __device__ __forceinline__ unsigned pk2(float lo, float hi) { return f2bf(lo) | (f2bf(hi) << 16); }
; __global__ void __launch_bounds__(512, 2) fwd_megakernel(Params Pk) {
;     ...
;         for (int row = gw; row < T; row += 4 * NW) {
;             f32x4 v[4][4];
; #pragma unroll
;             for (int r = 0; r < 4; ++r) { const int rr = (row + r * NW) < T ? (row + r * NW) : row; const float* src = (rr < TP ? P.xin0 : xin_hi) + (size_t)rr * D;
; #pragma unroll
;                 for (int k = 0; k < 4; ++k) v[r][k] = *(const f32x4*)(src + k * 256 + lane * 4); }
; #pragma unroll
;             for (int r = 0; r < 4; ++r) { const int rr = (row + r * NW) < T ? (row + r * NW) : row; float ss = 0.f;
; #pragma unroll
;                 for (int k = 0; k < 4; ++k) { const f32x4 q = v[r][k]; ss += (q[0] * q[0] + q[1] * q[1]) + (q[2] * q[2] + q[3] * q[3]);
;                     u32x2 w; w.x = pk2(q[0], q[1]); w.y = pk2(q[2], q[3]); *(u32x2*)(xb + (size_t)rr * D + k * 256 + lane * 4) = w; }
;                 ss = wave_sum(ss);
;                 if (lane < 4) rowss[(size_t)rr * 32 + lane] = lane == 0 ? ss : 0.f; }
;         }
.LBB0_58:
	v_cmp_gt_i32_e64 s[46:47], s7, v70
	v_ashrrev_i32_e32 v71, 31, v70
	v_lshlrev_b64 v[2:3], 12, v[70:71]
	v_cndmask_b32_e64 v1, v53, v55, s[46:47]
	v_cndmask_b32_e64 v0, v91, v92, s[46:47]
	v_lshl_add_u64 v[0:1], v[0:1], 0, v[2:3]
	v_lshl_add_u64 v[0:1], v[0:1], 0, v[58:59]
	global_load_dwordx4 v[102:105], v[0:1], off nt
	global_load_dwordx4 v[106:109], v[0:1], off offset:1024 nt
	global_load_dwordx4 v[110:113], v[0:1], off offset:2048 nt
	global_load_dwordx4 v[114:117], v[0:1], off offset:3072 nt
	v_add_u32_e32 v4, s18, v70
	v_cmp_gt_i32_e64 s[46:47], s6, v4
	v_lshlrev_b64 v[118:119], 11, v[70:71]
	v_lshl_add_u64 v[118:119], v[60:61], 0, v[118:119]
	v_cndmask_b32_e64 v68, v70, v4, s[46:47]
	v_cmp_gt_i32_e64 s[46:47], s7, v68
	v_ashrrev_i32_e32 v69, 31, v68
	v_add_u32_e32 v4, s18, v4
	v_cndmask_b32_e64 v1, v53, v55, s[46:47]
	v_cndmask_b32_e64 v0, v91, v92, s[46:47]
	v_lshlrev_b64 v[2:3], 12, v[68:69]
	v_cmp_gt_i32_e64 s[46:47], s6, v4
	v_lshl_add_u64 v[0:1], v[0:1], 0, v[2:3]
	v_lshl_add_u64 v[0:1], v[0:1], 0, v[58:59]
	v_cndmask_b32_e64 v66, v70, v4, s[46:47]
	v_cmp_gt_i32_e64 s[46:47], s7, v66
	v_ashrrev_i32_e32 v67, 31, v66
	v_add_u32_e32 v101, s18, v4
	global_load_dwordx4 v[44:47], v[0:1], off nt
	global_load_dwordx4 v[40:43], v[0:1], off offset:1024 nt
	global_load_dwordx4 v[36:39], v[0:1], off offset:2048 nt
	global_load_dwordx4 v[32:35], v[0:1], off offset:3072 nt
	v_cndmask_b32_e64 v1, v53, v55, s[46:47]
	v_cndmask_b32_e64 v0, v91, v92, s[46:47]
	v_lshlrev_b64 v[2:3], 12, v[66:67]
	v_cmp_gt_i32_e64 s[46:47], s6, v101
	v_lshl_add_u64 v[0:1], v[0:1], 0, v[2:3]
	v_lshl_add_u64 v[0:1], v[0:1], 0, v[58:59]
	v_cndmask_b32_e64 v64, v70, v101, s[46:47]
	v_cmp_gt_i32_e64 s[46:47], s7, v64
	v_ashrrev_i32_e32 v65, 31, v64
	global_load_dwordx4 v[28:31], v[0:1], off nt
	global_load_dwordx4 v[24:27], v[0:1], off offset:1024 nt
	global_load_dwordx4 v[20:23], v[0:1], off offset:2048 nt
	global_load_dwordx4 v[16:19], v[0:1], off offset:3072 nt
	v_cndmask_b32_e64 v1, v53, v55, s[46:47]
	v_cndmask_b32_e64 v0, v91, v92, s[46:47]
	v_lshlrev_b64 v[2:3], 12, v[64:65]
	v_lshl_add_u64 v[0:1], v[0:1], 0, v[2:3]
	v_lshl_add_u64 v[0:1], v[0:1], 0, v[58:59]
	global_load_dwordx4 v[12:15], v[0:1], off nt
	global_load_dwordx4 v[8:11], v[0:1], off offset:1024 nt
	s_waitcnt lgkmcnt(0)
	global_load_dwordx4 v[4:7], v[0:1], off offset:2048 nt
	s_nop 0
	global_load_dwordx4 v[0:3], v[0:1], off offset:3072 nt
	v_cmp_lt_i32_e64 s[46:47], v95, v94
	s_waitcnt vmcnt(15)
	v_mul_f32_e32 v120, v103, v103
	v_fmac_f32_e32 v120, v102, v102
	v_cvt_pk_bf16_f32 v102, v102, v103
	v_cvt_pk_bf16_f32 v103, v104, v105
	v_mul_f32_e32 v121, v105, v105
	global_store_dwordx2 v[118:119], v[102:103], off
	s_waitcnt vmcnt(15)
	v_mul_f32_e32 v102, v107, v107
	v_mul_f32_e32 v103, v109, v109
	v_fmac_f32_e32 v121, v104, v104
	v_fmac_f32_e32 v102, v106, v106
	v_fmac_f32_e32 v103, v108, v108
	v_add_f32_e32 v120, v120, v121
	v_add_f32_e32 v102, v102, v103
	v_add_f32_e32 v104, v120, v102
	v_cvt_pk_bf16_f32 v102, v106, v107
	v_cvt_pk_bf16_f32 v103, v108, v109
	global_store_dwordx2 v[118:119], v[102:103], off offset:512
	s_waitcnt vmcnt(15)
	v_mul_f32_e32 v102, v111, v111
	v_mul_f32_e32 v103, v113, v113
	v_fmac_f32_e32 v102, v110, v110
	v_fmac_f32_e32 v103, v112, v112
	v_add_f32_e32 v102, v102, v103
	v_add_f32_e32 v104, v104, v102
	v_cvt_pk_bf16_f32 v102, v110, v111
	v_cvt_pk_bf16_f32 v103, v112, v113
	global_store_dwordx2 v[118:119], v[102:103], off offset:1024
	s_waitcnt vmcnt(15)
	v_mul_f32_e32 v102, v115, v115
	v_mul_f32_e32 v103, v117, v117
	v_fmac_f32_e32 v102, v114, v114
	v_fmac_f32_e32 v103, v116, v116
	v_add_f32_e32 v102, v102, v103
	v_add_f32_e32 v104, v104, v102
	v_cvt_pk_bf16_f32 v102, v114, v115
	v_cvt_pk_bf16_f32 v103, v116, v117
	global_store_dwordx2 v[118:119], v[102:103], off offset:1536
	v_cndmask_b32_e64 v102, v93, v95, s[46:47]
	v_lshlrev_b32_e32 v102, 2, v102
	ds_bpermute_b32 v103, v102, v104
	v_cmp_lt_i32_e64 s[46:47], v96, v94
	s_waitcnt lgkmcnt(0)
	v_add_f32_e32 v104, v104, v103
	v_cndmask_b32_e64 v103, v93, v96, s[46:47]
	v_lshlrev_b32_e32 v103, 2, v103
	ds_bpermute_b32 v105, v103, v104
	v_cmp_lt_i32_e64 s[46:47], v97, v94
	s_waitcnt lgkmcnt(0)
	v_add_f32_e32 v105, v104, v105
	v_cndmask_b32_e64 v104, v93, v97, s[46:47]
	v_lshlrev_b32_e32 v104, 2, v104
	ds_bpermute_b32 v106, v104, v105
	v_cmp_lt_i32_e64 s[46:47], v98, v94
	s_waitcnt lgkmcnt(0)
	v_add_f32_e32 v106, v105, v106
	v_cndmask_b32_e64 v105, v93, v98, s[46:47]
	v_lshlrev_b32_e32 v105, 2, v105
	ds_bpermute_b32 v107, v105, v106
	v_cmp_lt_i32_e64 s[46:47], v99, v94
	s_waitcnt lgkmcnt(0)
	v_add_f32_e32 v107, v106, v107
	v_cndmask_b32_e64 v106, v93, v99, s[46:47]
	v_lshlrev_b32_e32 v106, 2, v106
	ds_bpermute_b32 v108, v106, v107
	v_cmp_lt_i32_e64 s[46:47], v100, v94
	s_waitcnt lgkmcnt(0)
	v_add_f32_e32 v108, v107, v108
	v_cndmask_b32_e64 v107, v93, v100, s[46:47]
	v_lshlrev_b32_e32 v107, 2, v107
	ds_bpermute_b32 v109, v107, v108
	s_and_saveexec_b64 s[4:5], vcc
	s_cbranch_execz .LBB0_60
	v_lshlrev_b64 v[70:71], 7, v[70:71]
	s_waitcnt lgkmcnt(0)
	v_add_f32_e32 v108, v108, v109
	v_lshl_add_u64 v[70:71], v[62:63], 0, v[70:71]
	v_cndmask_b32_e64 v108, 0, v108, s[44:45]
	global_store_dword v[70:71], v108, off
